# attention epilogue staged through LDS: bf16 o tile written per wave and read back row-major so each global store is a full 256-byte row segment (8 dwordx4 per wave instead of 32 dword)
# speedup vs baseline: 1.0060x; 1.0017x over previous
; __device__ __forceinline__ unsigned cvt_pk_bf16(float lo, float hi) { const f32x2 v = {lo, hi}; const bf16x2_t b = __builtin_convertvector(v, bf16x2_t); return __builtin_bit_cast(unsigned, b); }
; __device__ __forceinline__ int crow(int r, int hi) { return (r & 3) + 8 * (r >> 2) + 4 * hi; }
; __device__ __forceinline__ void attn_block(const Ptrs& P, int b, int h, int qb, LAS char* lds) {
;     ...
;     if (hi == 0) li_l[r32] = l_reg; asm volatile("s_waitcnt lgkmcnt(0)" ::: "memory");
;     float rli[16];
; #pragma unroll
;     for (int r = 0; r < 16; ++r) rli[r] = __builtin_amdgcn_rcpf(li_l[crow(r, hi)]);
;     const bool odd = (r32 & 1) != 0;
;     bf16* Ow = P.o_() + ((size_t)(b * SEQ + i0 + wid * QBLK + 4 * hi + (odd ? 1 : 0))) * DM + h * DV + (r32 & ~1);
; #pragma unroll
;     for (int r = 0; r < 16; r += 2) { const int rrow = (r & 3) + 8 * (r >> 2);
; #pragma unroll
;         for (int d0 = 0; d0 < 4; ++d0) { const float va = o[d0][r] * rli[r], vb = o[d0][r + 1] * rli[r + 1];
;             const float send = odd ? va : vb;
;             const float recv = __uint_as_float((unsigned)__builtin_amdgcn_update_dpp(0, (int)__float_as_uint(send), 0xB1  , 0xF, 0xF, false));
;             *(unsigned*)(Ow + (size_t)rrow * DM + d0 * 32) = odd ? cvt_pk_bf16(recv, vb) : cvt_pk_bf16(va, recv); } }
.LBB0_611:
	s_or_b64 exec, exec, s[22:23]
	s_waitcnt lgkmcnt(0)
	ds_read_b128 v[68:71], v193
	ds_read_b128 v[72:75], v193 offset:32
	ds_read_b128 v[76:79], v193 offset:64
	ds_read_b128 v[80:83], v193 offset:96
	s_mov_b64 s[22:23], 0
	s_mul_i32 s98, s6, 0x110
	s_mov_b64 s[100:101], 0x4000
	v_and_b32_e32 v86, 0xfff, v192
	v_and_b32_e32 v88, 30, v0
	v_and_b32_e32 v92, 63, v0
	v_or_b32_e32 v84, s74, v192
	v_add_u32_e32 v84, s6, v84
	v_sub_u32_e32 v84, v84, v86
	v_lshrrev_b32_e32 v89, 4, v92
	v_add_u32_e32 v84, v84, v89
	v_ashrrev_i32_e32 v85, 31, v84
	v_lshlrev_b64 v[84:85], 12, v[84:85]
	v_lshl_add_u64 v[90:91], v[172:173], 0, v[84:85]
	v_and_b32_e32 v92, 15, v92
	v_lshlrev_b32_e32 v84, 4, v92
	v_lshlrev_b32_e32 v85, 1, v88
	v_sub_u32_e32 v84, v84, v85
	v_ashrrev_i32_e32 v85, 31, v84
	v_lshl_add_u64 v[90:91], v[90:91], 0, v[84:85]
	v_mul_u32_u24_e32 v86, 0x110, v86
	v_lshl_add_u32 v86, v88, 1, v86
	v_add_u32_e32 v86, s98, v86
	v_mul_u32_u24_e32 v89, 0x110, v89
	v_lshl_add_u32 v89, v92, 4, v89
	v_add_u32_e32 v89, s98, v89
	v_mov_b32_e32 v87, 0x3020706
	v_mov_b32_e32 v88, 0x5040100
	s_nop 0
	v_cndmask_b32_e64 v87, v87, v88, s[4:5]
	s_waitcnt lgkmcnt(0)
	v_rcp_f32_e32 v68, v68
	v_rcp_f32_e32 v69, v69
	v_rcp_f32_e32 v70, v70
	v_rcp_f32_e32 v71, v71
	v_rcp_f32_e32 v72, v72
	v_rcp_f32_e32 v73, v73
	v_rcp_f32_e32 v74, v74
	v_rcp_f32_e32 v75, v75
	v_rcp_f32_e32 v76, v76
	v_rcp_f32_e32 v77, v77
	v_rcp_f32_e32 v78, v78
	v_rcp_f32_e32 v79, v79
	v_rcp_f32_e32 v80, v80
	v_rcp_f32_e32 v81, v81
	v_rcp_f32_e32 v82, v82
	v_rcp_f32_e32 v83, v83
	v_mul_f32_e32 v52, v52, v68
	v_mul_f32_e32 v53, v53, v69
	v_mul_f32_e32 v36, v36, v68
	v_mul_f32_e32 v37, v37, v69
	v_mul_f32_e32 v20, v20, v68
	v_mul_f32_e32 v21, v21, v69
	v_mul_f32_e32 v4, v4, v68
	v_mul_f32_e32 v5, v5, v69
	v_cvt_pk_bf16_f32 v52, v52, v53
	v_cvt_pk_bf16_f32 v36, v36, v37
	v_cvt_pk_bf16_f32 v20, v20, v21
	v_cvt_pk_bf16_f32 v4, v4, v5
	s_nop 0
	v_mov_b32_dpp v53, v52 quad_perm:[1,0,3,2] row_mask:0xf bank_mask:0xf
	v_mov_b32_dpp v37, v36 quad_perm:[1,0,3,2] row_mask:0xf bank_mask:0xf
	v_mov_b32_dpp v21, v20 quad_perm:[1,0,3,2] row_mask:0xf bank_mask:0xf
	v_mov_b32_dpp v5, v4 quad_perm:[1,0,3,2] row_mask:0xf bank_mask:0xf
	v_perm_b32 v52, v53, v52, v87
	v_perm_b32 v36, v37, v36, v87
	v_perm_b32 v20, v21, v20, v87
	v_perm_b32 v4, v5, v4, v87
	ds_write_b32 v86, v52 offset:0
	ds_write_b32 v86, v36 offset:64
	ds_write_b32 v86, v20 offset:128
	ds_write_b32 v86, v4 offset:192
	v_mul_f32_e32 v54, v54, v70
	v_mul_f32_e32 v55, v55, v71
	v_mul_f32_e32 v38, v38, v70
	v_mul_f32_e32 v39, v39, v71
	v_mul_f32_e32 v22, v22, v70
	v_mul_f32_e32 v23, v23, v71
	v_mul_f32_e32 v6, v6, v70
	v_mul_f32_e32 v7, v7, v71
	v_cvt_pk_bf16_f32 v54, v54, v55
	v_cvt_pk_bf16_f32 v38, v38, v39
	v_cvt_pk_bf16_f32 v22, v22, v23
	v_cvt_pk_bf16_f32 v6, v6, v7
	s_nop 0
	v_mov_b32_dpp v55, v54 quad_perm:[1,0,3,2] row_mask:0xf bank_mask:0xf
	v_mov_b32_dpp v39, v38 quad_perm:[1,0,3,2] row_mask:0xf bank_mask:0xf
	v_mov_b32_dpp v23, v22 quad_perm:[1,0,3,2] row_mask:0xf bank_mask:0xf
	v_mov_b32_dpp v7, v6 quad_perm:[1,0,3,2] row_mask:0xf bank_mask:0xf
	v_perm_b32 v54, v55, v54, v87
	v_perm_b32 v38, v39, v38, v87
	v_perm_b32 v22, v23, v22, v87
	v_perm_b32 v6, v7, v6, v87
	ds_write_b32 v86, v54 offset:544
	ds_write_b32 v86, v38 offset:608
	ds_write_b32 v86, v22 offset:672
	ds_write_b32 v86, v6 offset:736
	v_mul_f32_e32 v56, v56, v72
	v_mul_f32_e32 v57, v57, v73
	v_mul_f32_e32 v40, v40, v72
	v_mul_f32_e32 v41, v41, v73
	v_mul_f32_e32 v24, v24, v72
	v_mul_f32_e32 v25, v25, v73
	v_mul_f32_e32 v8, v8, v72
	v_mul_f32_e32 v9, v9, v73
	v_cvt_pk_bf16_f32 v56, v56, v57
	v_cvt_pk_bf16_f32 v40, v40, v41
	v_cvt_pk_bf16_f32 v24, v24, v25
	v_cvt_pk_bf16_f32 v8, v8, v9
	s_nop 0
	v_mov_b32_dpp v57, v56 quad_perm:[1,0,3,2] row_mask:0xf bank_mask:0xf
	v_mov_b32_dpp v41, v40 quad_perm:[1,0,3,2] row_mask:0xf bank_mask:0xf
	v_mov_b32_dpp v25, v24 quad_perm:[1,0,3,2] row_mask:0xf bank_mask:0xf
	v_mov_b32_dpp v9, v8 quad_perm:[1,0,3,2] row_mask:0xf bank_mask:0xf
	v_perm_b32 v56, v57, v56, v87
	v_perm_b32 v40, v41, v40, v87
	v_perm_b32 v24, v25, v24, v87
	v_perm_b32 v8, v9, v8, v87
	ds_write_b32 v86, v56 offset:2176
	ds_write_b32 v86, v40 offset:2240
	ds_write_b32 v86, v24 offset:2304
	ds_write_b32 v86, v8 offset:2368
	v_mul_f32_e32 v58, v58, v74
	v_mul_f32_e32 v59, v59, v75
	v_mul_f32_e32 v42, v42, v74
	v_mul_f32_e32 v43, v43, v75
	v_mul_f32_e32 v26, v26, v74
	v_mul_f32_e32 v27, v27, v75
	v_mul_f32_e32 v10, v10, v74
	v_mul_f32_e32 v11, v11, v75
	v_cvt_pk_bf16_f32 v58, v58, v59
	v_cvt_pk_bf16_f32 v42, v42, v43
	v_cvt_pk_bf16_f32 v26, v26, v27
	v_cvt_pk_bf16_f32 v10, v10, v11
	s_nop 0
	v_mov_b32_dpp v59, v58 quad_perm:[1,0,3,2] row_mask:0xf bank_mask:0xf
	v_mov_b32_dpp v43, v42 quad_perm:[1,0,3,2] row_mask:0xf bank_mask:0xf
	v_mov_b32_dpp v27, v26 quad_perm:[1,0,3,2] row_mask:0xf bank_mask:0xf
	v_mov_b32_dpp v11, v10 quad_perm:[1,0,3,2] row_mask:0xf bank_mask:0xf
	v_perm_b32 v58, v59, v58, v87
	v_perm_b32 v42, v43, v42, v87
	v_perm_b32 v26, v27, v26, v87
	v_perm_b32 v10, v11, v10, v87
	ds_write_b32 v86, v58 offset:2720
	ds_write_b32 v86, v42 offset:2784
	ds_write_b32 v86, v26 offset:2848
; __device__ __forceinline__ unsigned cvt_pk_bf16(float lo, float hi) { const f32x2 v = {lo, hi}; const bf16x2_t b = __builtin_convertvector(v, bf16x2_t); return __builtin_bit_cast(unsigned, b); }
; __device__ __forceinline__ void attn_block(const Ptrs& P, int b, int h, int qb, LAS char* lds) {
;     ...
;     for (int r = 0; r < 16; r += 2) { const int rrow = (r & 3) + 8 * (r >> 2);
; #pragma unroll
;         for (int d0 = 0; d0 < 4; ++d0) { const float va = o[d0][r] * rli[r], vb = o[d0][r + 1] * rli[r + 1];
;             const float send = odd ? va : vb;
;             const float recv = __uint_as_float((unsigned)__builtin_amdgcn_update_dpp(0, (int)__float_as_uint(send), 0xB1  , 0xF, 0xF, false));
;             *(unsigned*)(Ow + (size_t)rrow * DM + d0 * 32) = odd ? cvt_pk_bf16(recv, vb) : cvt_pk_bf16(va, recv); } }
;     __syncthreads();
	ds_write_b32 v86, v10 offset:2912
	v_mul_f32_e32 v60, v60, v76
	v_mul_f32_e32 v61, v61, v77
	v_mul_f32_e32 v44, v44, v76
	v_mul_f32_e32 v45, v45, v77
	v_mul_f32_e32 v28, v28, v76
	v_mul_f32_e32 v29, v29, v77
	v_mul_f32_e32 v12, v12, v76
	v_mul_f32_e32 v13, v13, v77
	v_cvt_pk_bf16_f32 v60, v60, v61
	v_cvt_pk_bf16_f32 v44, v44, v45
	v_cvt_pk_bf16_f32 v28, v28, v29
	v_cvt_pk_bf16_f32 v12, v12, v13
	s_nop 0
	v_mov_b32_dpp v61, v60 quad_perm:[1,0,3,2] row_mask:0xf bank_mask:0xf
	v_mov_b32_dpp v45, v44 quad_perm:[1,0,3,2] row_mask:0xf bank_mask:0xf
	v_mov_b32_dpp v29, v28 quad_perm:[1,0,3,2] row_mask:0xf bank_mask:0xf
	v_mov_b32_dpp v13, v12 quad_perm:[1,0,3,2] row_mask:0xf bank_mask:0xf
	v_perm_b32 v60, v61, v60, v87
	v_perm_b32 v44, v45, v44, v87
	v_perm_b32 v28, v29, v28, v87
	v_perm_b32 v12, v13, v12, v87
	ds_write_b32 v86, v60 offset:4352
	ds_write_b32 v86, v44 offset:4416
	ds_write_b32 v86, v28 offset:4480
	ds_write_b32 v86, v12 offset:4544
	v_mul_f32_e32 v62, v62, v78
	v_mul_f32_e32 v63, v63, v79
	v_mul_f32_e32 v46, v46, v78
	v_mul_f32_e32 v47, v47, v79
	v_mul_f32_e32 v30, v30, v78
	v_mul_f32_e32 v31, v31, v79
	v_mul_f32_e32 v14, v14, v78
	v_mul_f32_e32 v15, v15, v79
	v_cvt_pk_bf16_f32 v62, v62, v63
	v_cvt_pk_bf16_f32 v46, v46, v47
	v_cvt_pk_bf16_f32 v30, v30, v31
	v_cvt_pk_bf16_f32 v14, v14, v15
	s_nop 0
	v_mov_b32_dpp v63, v62 quad_perm:[1,0,3,2] row_mask:0xf bank_mask:0xf
	v_mov_b32_dpp v47, v46 quad_perm:[1,0,3,2] row_mask:0xf bank_mask:0xf
	v_mov_b32_dpp v31, v30 quad_perm:[1,0,3,2] row_mask:0xf bank_mask:0xf
	v_mov_b32_dpp v15, v14 quad_perm:[1,0,3,2] row_mask:0xf bank_mask:0xf
	v_perm_b32 v62, v63, v62, v87
	v_perm_b32 v46, v47, v46, v87
	v_perm_b32 v30, v31, v30, v87
	v_perm_b32 v14, v15, v14, v87
	ds_write_b32 v86, v62 offset:4896
	ds_write_b32 v86, v46 offset:4960
	ds_write_b32 v86, v30 offset:5024
	ds_write_b32 v86, v14 offset:5088
	v_mul_f32_e32 v64, v64, v80
	v_mul_f32_e32 v65, v65, v81
	v_mul_f32_e32 v48, v48, v80
	v_mul_f32_e32 v49, v49, v81
	v_mul_f32_e32 v32, v32, v80
	v_mul_f32_e32 v33, v33, v81
	v_mul_f32_e32 v16, v16, v80
	v_mul_f32_e32 v17, v17, v81
	v_cvt_pk_bf16_f32 v64, v64, v65
	v_cvt_pk_bf16_f32 v48, v48, v49
	v_cvt_pk_bf16_f32 v32, v32, v33
	v_cvt_pk_bf16_f32 v16, v16, v17
	s_nop 0
	v_mov_b32_dpp v65, v64 quad_perm:[1,0,3,2] row_mask:0xf bank_mask:0xf
	v_mov_b32_dpp v49, v48 quad_perm:[1,0,3,2] row_mask:0xf bank_mask:0xf
	v_mov_b32_dpp v33, v32 quad_perm:[1,0,3,2] row_mask:0xf bank_mask:0xf
	v_mov_b32_dpp v17, v16 quad_perm:[1,0,3,2] row_mask:0xf bank_mask:0xf
	v_perm_b32 v64, v65, v64, v87
	v_perm_b32 v48, v49, v48, v87
	v_perm_b32 v32, v33, v32, v87
	v_perm_b32 v16, v17, v16, v87
	ds_write_b32 v86, v64 offset:6528
	ds_write_b32 v86, v48 offset:6592
	ds_write_b32 v86, v32 offset:6656
	ds_write_b32 v86, v16 offset:6720
	v_mul_f32_e32 v66, v66, v82
	v_mul_f32_e32 v67, v67, v83
	v_mul_f32_e32 v50, v50, v82
	v_mul_f32_e32 v51, v51, v83
	v_mul_f32_e32 v34, v34, v82
	v_mul_f32_e32 v35, v35, v83
	v_mul_f32_e32 v18, v18, v82
	v_mul_f32_e32 v19, v19, v83
	v_cvt_pk_bf16_f32 v66, v66, v67
	v_cvt_pk_bf16_f32 v50, v50, v51
	v_cvt_pk_bf16_f32 v34, v34, v35
	v_cvt_pk_bf16_f32 v18, v18, v19
	s_nop 0
	v_mov_b32_dpp v67, v66 quad_perm:[1,0,3,2] row_mask:0xf bank_mask:0xf
	v_mov_b32_dpp v51, v50 quad_perm:[1,0,3,2] row_mask:0xf bank_mask:0xf
	v_mov_b32_dpp v35, v34 quad_perm:[1,0,3,2] row_mask:0xf bank_mask:0xf
	v_mov_b32_dpp v19, v18 quad_perm:[1,0,3,2] row_mask:0xf bank_mask:0xf
	v_perm_b32 v66, v67, v66, v87
	v_perm_b32 v50, v51, v50, v87
	v_perm_b32 v34, v35, v34, v87
	v_perm_b32 v18, v19, v18, v87
	ds_write_b32 v86, v66 offset:7072
	ds_write_b32 v86, v50 offset:7136
	ds_write_b32 v86, v34 offset:7200
	ds_write_b32 v86, v18 offset:7264
	s_waitcnt lgkmcnt(0)
	ds_read_b128 v[200:203], v89 offset:0
	ds_read_b128 v[204:207], v89 offset:1088
	ds_read_b128 v[208:211], v89 offset:2176
	ds_read_b128 v[212:215], v89 offset:3264
	s_waitcnt lgkmcnt(3)
	global_store_dwordx4 v[90:91], v[200:203], off
	s_nop 1
	v_lshl_add_u64 v[90:91], v[90:91], 0, s[100:101]
	s_waitcnt lgkmcnt(2)
	global_store_dwordx4 v[90:91], v[204:207], off
	s_nop 1
	v_lshl_add_u64 v[90:91], v[90:91], 0, s[100:101]
	s_waitcnt lgkmcnt(1)
	global_store_dwordx4 v[90:91], v[208:211], off
	s_nop 1
	v_lshl_add_u64 v[90:91], v[90:91], 0, s[100:101]
	s_waitcnt lgkmcnt(0)
	global_store_dwordx4 v[90:91], v[212:215], off
	s_nop 1
	v_lshl_add_u64 v[90:91], v[90:91], 0, s[100:101]
	ds_read_b128 v[200:203], v89 offset:4352
	ds_read_b128 v[204:207], v89 offset:5440
	ds_read_b128 v[208:211], v89 offset:6528
	ds_read_b128 v[212:215], v89 offset:7616
	s_waitcnt lgkmcnt(3)
	global_store_dwordx4 v[90:91], v[200:203], off
	s_nop 1
	v_lshl_add_u64 v[90:91], v[90:91], 0, s[100:101]
	s_waitcnt lgkmcnt(2)
	global_store_dwordx4 v[90:91], v[204:207], off
	s_nop 1
	v_lshl_add_u64 v[90:91], v[90:91], 0, s[100:101]
	s_waitcnt lgkmcnt(1)
	global_store_dwordx4 v[90:91], v[208:211], off
	s_nop 1
	v_lshl_add_u64 v[90:91], v[90:91], 0, s[100:101]
	s_waitcnt lgkmcnt(0)
	global_store_dwordx4 v[90:91], v[212:215], off
	s_nop 1
	v_lshl_add_u64 v[90:91], v[90:91], 0, s[100:101]
	s_and_b64 vcc, exec, s[36:37]
	s_barrier
	s_cbranch_vccnz .LBB0_609
